# attention-phase TR units: W2in (gain) transpose loop also issues its 8 gain + 8 data loads together
# baseline (speedup 1.0000x reference)
; #define LAS __attribute__((address_space(3)))
; __device__ __forceinline__ void tr_item(const float* __restrict__ W, int K, int N, bf16_t* __restrict__ WT, const float* __restrict__ gain, int mode, LAS float* scr, int item, int lane) {
;     const int nblk = N / 64, kb = item / nblk, nb = item % nblk, k0 = 64 * kb, n0 = 64 * nb;
;     int src0 = n0; float cs = 1.f;
;     if (mode == 1) { const int pn = n0 >> 8, w = n0 & 255; src0 = (w >> 7) * DFF + pn * 128 + (w & 127); }
;     if (mode == 2 && n0 < 1024) cs = QSCALE_A;
;     const int lk = lane >> 4, ln = (lane & 15) * 4;
; #pragma unroll 8
;     for (int i = 0; i < 16; ++i) { const int kk = 4 * i + lk; const float g = gain ? gain[k0 + kk] * cs : cs; const f32x4 v = __builtin_nontemporal_load((const f32x4*)(W + (size_t)(k0 + kk) * N + src0 + ln));
;         LAS float* d = scr + kk * 65 + ln; d[0] = v.x * g; d[1] = v.y * g; d[2] = v.z * g; d[3] = v.w * g; }
;     asm volatile("s_waitcnt lgkmcnt(0)" ::: "memory");
.LBB0_383:
	s_andn2_b64 vcc, exec, s[2:3]
	s_cbranch_vccnz .LBB0_403
	s_mov_b64 s[2:3], s[68:69]
	s_mul_hi_i32 s5, s4, 0x2e8ba2e9
	s_load_dwordx2 s[16:17], s[2:3], 0x70
	s_mov_b64 s[2:3], s[68:69]
	s_lshr_b32 s6, s5, 31
	s_ashr_i32 s5, s5, 5
	s_add_i32 s5, s5, s6
	s_load_dwordx2 s[2:3], s[2:3], 0x68
	s_mul_i32 s6, s5, 0xb0
	s_sub_i32 s6, s4, s6
	s_lshl_b32 s4, s5, 6
	s_bfe_i32 s5, s6, 0x10001
	s_lshl_b32 s15, s6, 6
	s_and_b32 s18, s5, 0x1600
	s_lshl_b32 s5, s6, 5
	s_and_b32 s19, s5, 0xffffff80
	s_and_b32 s20, s15, 64
	s_waitcnt lgkmcnt(0)
	s_cmp_lg_u64 s[2:3], 0
	s_cselect_b64 s[8:9], -1, 0
	s_add_i32 s18, s18, s19
	v_lshl_add_u64 v[64:65], s[16:17], 0, v[10:11]
	s_or_b32 s16, s18, s20
	s_ashr_i32 s17, s16, 31
	s_lshl_b64 s[16:17], s[16:17], 2
	v_or_b32_e32 v0, s4, v81
	v_mov_b64_e32 v[68:69], s[16:17]
	v_mad_i64_i32 v[48:49], s[16:17], v0, s85, v[68:69]
	v_or_b32_e32 v0, s4, v82
	v_mad_i64_i32 v[52:53], s[16:17], v0, s85, v[68:69]
	v_or_b32_e32 v0, s4, v83
	v_mad_i64_i32 v[54:55], s[16:17], v0, s85, v[68:69]
	v_or_b32_e32 v0, s4, v84
	v_mad_i64_i32 v[56:57], s[16:17], v0, s85, v[68:69]
	v_or_b32_e32 v0, s4, v85
	s_ashr_i32 s5, s4, 31
	v_mad_i64_i32 v[58:59], s[16:17], v0, s85, v[68:69]
	v_or_b32_e32 v0, s4, v86
	v_mov_b32_e32 v67, s5
	v_or_b32_e32 v66, s4, v2
	v_mad_i64_i32 v[60:61], s[16:17], v0, s85, v[68:69]
	v_or_b32_e32 v0, s4, v87
	v_lshlrev_b64 v[50:51], 2, v[66:67]
	v_mad_i64_i32 v[62:63], s[16:17], v0, s85, v[68:69]
	v_ashrrev_i32_e32 v67, 31, v66
	v_mad_i64_i32 v[68:69], s[16:17], v66, s85, v[68:69]
	s_mov_b64 s[6:7], 0
	v_lshl_add_u64 v[48:49], v[64:65], 0, v[48:49]
	v_lshl_add_u64 v[52:53], v[64:65], 0, v[52:53]
	v_lshl_add_u64 v[54:55], v[64:65], 0, v[54:55]
	v_lshl_add_u64 v[56:57], v[64:65], 0, v[56:57]
	v_lshl_add_u64 v[58:59], v[64:65], 0, v[58:59]
	v_lshl_add_u64 v[60:61], v[64:65], 0, v[60:61]
	v_lshl_add_u64 v[62:63], v[64:65], 0, v[62:63]
	v_lshl_add_u64 v[64:65], v[64:65], 0, v[68:69]
	v_lshlrev_b64 v[66:67], 2, v[66:67]
	v_mov_b32_e32 v88, v80
	s_and_b64 vcc, exec, s[8:9]
	s_cbranch_vccz .LBB0_386
.Ltr1_loop:
	v_lshl_add_u64 v[68:69], s[2:3], 0, v[50:51]
	global_load_dword v132, v[68:69], off
	global_load_dword v134, v[68:69], off offset:16
	global_load_dword v136, v[68:69], off offset:32
	global_load_dword v138, v[68:69], off offset:48
	global_load_dword v140, v[68:69], off offset:64
	global_load_dword v142, v[68:69], off offset:80
	global_load_dword v144, v[68:69], off offset:96
	global_load_dword v146, v[68:69], off offset:112
	v_lshl_add_u64 v[90:91], v[64:65], 0, s[6:7]
	global_load_dwordx4 v[100:103], v[90:91], off nt
	v_lshl_add_u64 v[92:93], v[62:63], 0, s[6:7]
	global_load_dwordx4 v[104:107], v[92:93], off nt
	v_lshl_add_u64 v[90:91], v[60:61], 0, s[6:7]
	global_load_dwordx4 v[108:111], v[90:91], off nt
	v_lshl_add_u64 v[92:93], v[58:59], 0, s[6:7]
	global_load_dwordx4 v[112:115], v[92:93], off nt
	v_lshl_add_u64 v[90:91], v[56:57], 0, s[6:7]
	global_load_dwordx4 v[116:119], v[90:91], off nt
	v_lshl_add_u64 v[92:93], v[54:55], 0, s[6:7]
	global_load_dwordx4 v[120:123], v[92:93], off nt
	v_lshl_add_u64 v[90:91], v[52:53], 0, s[6:7]
	global_load_dwordx4 v[124:127], v[90:91], off nt
	v_lshl_add_u64 v[92:93], v[48:49], 0, s[6:7]
	global_load_dwordx4 v[128:131], v[92:93], off nt
	s_add_u32 s6, s6, 0x160000
	s_addc_u32 s7, s7, 0
	s_add_u32 s2, s2, 0x80
	s_addc_u32 s3, s3, 0
	s_waitcnt vmcnt(7)
	v_pk_mul_f32 v[90:91], v[132:133], v[100:101] op_sel_hi:[0,1]
	v_pk_mul_f32 v[92:93], v[132:133], v[102:103] op_sel_hi:[0,1]
	ds_write2_b32 v88, v92, v93 offset0:2 offset1:3
	ds_write2_b32 v88, v90, v91 offset1:1
	s_waitcnt vmcnt(6)
	v_pk_mul_f32 v[90:91], v[134:135], v[104:105] op_sel_hi:[0,1]
	v_pk_mul_f32 v[92:93], v[134:135], v[106:107] op_sel_hi:[0,1]
	v_add_u32_e32 v70, 0x410, v88
	v_add_u32_e32 v89, 0x418, v88
	ds_write2_b32 v70, v90, v91 offset1:1
	ds_write2_b32 v89, v92, v93 offset1:1
	s_waitcnt vmcnt(5)
	v_pk_mul_f32 v[90:91], v[136:137], v[108:109] op_sel_hi:[0,1]
	v_pk_mul_f32 v[92:93], v[136:137], v[110:111] op_sel_hi:[0,1]
	v_add_u32_e32 v70, 0x820, v88
	v_add_u32_e32 v89, 0x828, v88
	ds_write2_b32 v70, v90, v91 offset1:1
	ds_write2_b32 v89, v92, v93 offset1:1
	s_waitcnt vmcnt(4)
	v_pk_mul_f32 v[90:91], v[138:139], v[112:113] op_sel_hi:[0,1]
	v_pk_mul_f32 v[92:93], v[138:139], v[114:115] op_sel_hi:[0,1]
	v_add_u32_e32 v70, 0xc30, v88
	v_add_u32_e32 v89, 0xc38, v88
	ds_write2_b32 v70, v90, v91 offset1:1
	ds_write2_b32 v89, v92, v93 offset1:1
	s_waitcnt vmcnt(3)
	v_pk_mul_f32 v[90:91], v[140:141], v[116:117] op_sel_hi:[0,1]
	v_pk_mul_f32 v[92:93], v[140:141], v[118:119] op_sel_hi:[0,1]
	v_add_u32_e32 v70, 0x1040, v88
	v_add_u32_e32 v89, 0x1048, v88
	ds_write2_b32 v70, v90, v91 offset1:1
	ds_write2_b32 v89, v92, v93 offset1:1
	s_waitcnt vmcnt(2)
	v_pk_mul_f32 v[90:91], v[142:143], v[120:121] op_sel_hi:[0,1]
	v_pk_mul_f32 v[92:93], v[142:143], v[122:123] op_sel_hi:[0,1]
	v_add_u32_e32 v70, 0x1450, v88
	v_add_u32_e32 v89, 0x1458, v88
	ds_write2_b32 v70, v90, v91 offset1:1
	ds_write2_b32 v89, v92, v93 offset1:1
	s_waitcnt vmcnt(1)
	v_pk_mul_f32 v[90:91], v[144:145], v[124:125] op_sel_hi:[0,1]
	v_pk_mul_f32 v[92:93], v[144:145], v[126:127] op_sel_hi:[0,1]
	v_add_u32_e32 v70, 0x1860, v88
	v_add_u32_e32 v89, 0x1868, v88
	ds_write2_b32 v70, v90, v91 offset1:1
	ds_write2_b32 v89, v92, v93 offset1:1
	s_waitcnt vmcnt(0)
	v_pk_mul_f32 v[90:91], v[146:147], v[128:129] op_sel_hi:[0,1]
	v_pk_mul_f32 v[92:93], v[146:147], v[130:131] op_sel_hi:[0,1]
	v_add_u32_e32 v70, 0x1c70, v88
	v_add_u32_e32 v89, 0x1c78, v88
	ds_write2_b32 v70, v90, v91 offset1:1
	ds_write2_b32 v89, v92, v93 offset1:1
	v_add_u32_e32 v88, 0x2080, v88
	s_cmp_lg_u32 s6, 0x2c0000
	s_cbranch_scc1 .Ltr1_loop
	s_branch .LBB0_402
